# same MFMA-shadow B0 fragment prefetch applied to the 4 DN K-loops (label moved below the first-iteration reads, lgkmcnt(0) at epilogue entry)
# baseline (speedup 1.0000x reference)
; #define PG8_STAGE(bufoff, gbase, voff) do { _Pragma("unroll") for (int _i = 0; _i < 2; ++_i) \
;         __builtin_amdgcn_global_load_lds((const unsigned*)((const char*)(gbase) + (voff)[_i]), (LAS unsigned*)(lds + (bufoff) + ldsw + _i * 8192), 16, 0, 0); } while (0)
; #define PG8_LDA(dst, b, h) do { _Pragma("unroll") for (int m = 0; m < 4; ++m) _Pragma("unroll") for (int k = 0; k < 2; ++k) dst[m][k] = *(const LAS bf16x8*)(lds + PG8_SA(b, h) + aoff + m * 2048 + k * 1024); } while (0)
; #define PG8_LDB(dst, b, h) do { _Pragma("unroll") for (int n = 0; n < 2; ++n) _Pragma("unroll") for (int k = 0; k < 2; ++k) dst[n][k] = *(const LAS bf16x8*)(lds + PG8_SB(b, h) + boff + n * 2048 + k * 1024); } while (0)
; #define PG8_SCHED __builtin_amdgcn_sched_barrier(0)
; template <class Epi>
; __device__ __forceinline__ void gemm_phase(LAS unsigned char* lds, const int tid, const Gemm g, const StaticOrder& S, const Epi& E) {
;     ...
;     f32x4 acc[2][2][4][2];
; #pragma unroll
;     for (int a = 0; a < 2; ++a)
; #pragma unroll
;         for (int b = 0; b < 2; ++b)
; #pragma unroll
;             for (int m = 0; m < 4; ++m)
; #pragma unroll
;                 for (int n = 0; n < 2; ++n) acc[a][b][m][n] = (f32x4){0.f, 0.f, 0.f, 0.f};
;     ...
;             PG8_LDB(B0, 0, 0); PG8_LDB(B1, 0, 1); PG8_SCHED; PG8_LDA(At, 0, 0); PG8_STAGE(PG8_SA(1, 1), a1 + hstepA, voffA);
.LBB0_350:
	v_mov_b32_e32 v179, 0
	s_andn2_b64 vcc, exec, s[20:21]
	v_mov_b32_e32 v178, 0
	v_mov_b32_e32 v181, 0
	v_mov_b32_e32 v180, 0
	v_mov_b32_e32 v183, 0
	v_mov_b32_e32 v182, 0
	v_mov_b32_e32 v185, 0
	v_mov_b32_e32 v184, 0
	v_mov_b32_e32 v177, 0
	v_mov_b32_e32 v176, 0
	v_mov_b32_e32 v175, 0
	v_mov_b32_e32 v174, 0
	v_mov_b32_e32 v173, 0
	v_mov_b32_e32 v172, 0
	v_mov_b32_e32 v171, 0
	v_mov_b32_e32 v170, 0
	v_mov_b32_e32 v161, 0
	v_mov_b32_e32 v160, 0
	v_mov_b32_e32 v159, 0
	v_mov_b32_e32 v158, 0
	v_mov_b32_e32 v157, 0
	v_mov_b32_e32 v156, 0
	v_mov_b32_e32 v155, 0
	v_mov_b32_e32 v154, 0
	v_mov_b32_e32 v145, 0
	v_mov_b32_e32 v144, 0
	v_mov_b32_e32 v127, 0
	v_mov_b32_e32 v126, 0
	v_mov_b32_e32 v125, 0
	v_mov_b32_e32 v124, 0
	v_mov_b32_e32 v123, 0
	v_mov_b32_e32 v122, 0
	v_mov_b32_e32 v193, 0
	v_mov_b32_e32 v192, 0
	v_mov_b32_e32 v191, 0
	v_mov_b32_e32 v190, 0
	v_mov_b32_e32 v189, 0
	v_mov_b32_e32 v188, 0
	v_mov_b32_e32 v187, 0
	v_mov_b32_e32 v186, 0
	v_mov_b32_e32 v169, 0
	v_mov_b32_e32 v168, 0
	v_mov_b32_e32 v167, 0
	v_mov_b32_e32 v166, 0
	v_mov_b32_e32 v165, 0
	v_mov_b32_e32 v164, 0
	v_mov_b32_e32 v163, 0
	v_mov_b32_e32 v162, 0
	v_mov_b32_e32 v153, 0
	v_mov_b32_e32 v152, 0
	v_mov_b32_e32 v151, 0
	v_mov_b32_e32 v150, 0
	v_mov_b32_e32 v149, 0
	v_mov_b32_e32 v148, 0
	v_mov_b32_e32 v147, 0
	v_mov_b32_e32 v146, 0
	v_mov_b32_e32 v121, 0
	v_mov_b32_e32 v120, 0
	v_mov_b32_e32 v119, 0
	v_mov_b32_e32 v118, 0
	v_mov_b32_e32 v117, 0
	v_mov_b32_e32 v116, 0
	v_mov_b32_e32 v115, 0
	v_mov_b32_e32 v114, 0
	v_mov_b32_e32 v97, 0
	v_mov_b32_e32 v96, 0
	v_mov_b32_e32 v99, 0
	v_mov_b32_e32 v98, 0
	v_mov_b32_e32 v101, 0
	v_mov_b32_e32 v100, 0
	v_mov_b32_e32 v103, 0
	v_mov_b32_e32 v102, 0
	v_mov_b32_e32 v95, 0
	v_mov_b32_e32 v94, 0
	v_mov_b32_e32 v93, 0
	v_mov_b32_e32 v92, 0
	v_mov_b32_e32 v91, 0
	v_mov_b32_e32 v90, 0
	v_mov_b32_e32 v89, 0
	v_mov_b32_e32 v88, 0
	v_mov_b32_e32 v79, 0
	v_mov_b32_e32 v78, 0
	v_mov_b32_e32 v77, 0
	v_mov_b32_e32 v76, 0
	v_mov_b32_e32 v75, 0
	v_mov_b32_e32 v74, 0
	v_mov_b32_e32 v73, 0
	v_mov_b32_e32 v72, 0
	v_mov_b32_e32 v63, 0
	v_mov_b32_e32 v62, 0
	v_mov_b32_e32 v61, 0
	v_mov_b32_e32 v60, 0
	v_mov_b32_e32 v59, 0
	v_mov_b32_e32 v58, 0
	v_mov_b32_e32 v57, 0
	v_mov_b32_e32 v56, 0
	v_mov_b32_e32 v111, 0
	v_mov_b32_e32 v110, 0
	v_mov_b32_e32 v109, 0
	v_mov_b32_e32 v108, 0
	v_mov_b32_e32 v107, 0
	v_mov_b32_e32 v106, 0
	v_mov_b32_e32 v105, 0
	v_mov_b32_e32 v104, 0
	v_mov_b32_e32 v87, 0
	v_mov_b32_e32 v86, 0
	v_mov_b32_e32 v85, 0
	v_mov_b32_e32 v84, 0
	v_mov_b32_e32 v83, 0
	v_mov_b32_e32 v82, 0
	v_mov_b32_e32 v81, 0
	v_mov_b32_e32 v80, 0
	v_mov_b32_e32 v71, 0
	v_mov_b32_e32 v70, 0
	v_mov_b32_e32 v69, 0
	v_mov_b32_e32 v68, 0
	v_mov_b32_e32 v67, 0
	v_mov_b32_e32 v66, 0
	v_mov_b32_e32 v65, 0
	v_mov_b32_e32 v64, 0
	v_mov_b32_e32 v55, 0
	v_mov_b32_e32 v54, 0
	v_mov_b32_e32 v53, 0
	v_mov_b32_e32 v52, 0
	v_mov_b32_e32 v51, 0
	v_mov_b32_e32 v50, 0
	v_mov_b32_e32 v49, 0
	v_mov_b32_e32 v48, 0
	s_cbranch_vccnz .LBB0_354
	s_add_u32 s58, s28, 0x100
	v_mov_b32_e32 v0, 0
	v_mov_b32_e32 v1, 0
	s_addc_u32 s59, s29, 0
	s_mov_b32 s30, 0
	v_pk_mov_b32 v[2:3], v[0:1], v[0:1]
	v_pk_mov_b32 v[4:5], v[0:1], v[0:1]
	v_pk_mov_b32 v[6:7], v[0:1], v[0:1]
	v_pk_mov_b32 v[8:9], v[0:1], v[0:1]
	v_pk_mov_b32 v[10:11], v[0:1], v[0:1]
	v_pk_mov_b32 v[12:13], v[0:1], v[0:1]
	v_pk_mov_b32 v[14:15], v[0:1], v[0:1]
	v_pk_mov_b32 v[16:17], v[0:1], v[0:1]
	v_pk_mov_b32 v[18:19], v[0:1], v[0:1]
	v_pk_mov_b32 v[20:21], v[0:1], v[0:1]
	v_pk_mov_b32 v[22:23], v[0:1], v[0:1]
	v_pk_mov_b32 v[24:25], v[0:1], v[0:1]
	v_pk_mov_b32 v[26:27], v[0:1], v[0:1]
	v_pk_mov_b32 v[28:29], v[0:1], v[0:1]
	v_pk_mov_b32 v[30:31], v[0:1], v[0:1]
	v_pk_mov_b32 v[32:33], v[0:1], v[0:1]
	v_pk_mov_b32 v[34:35], v[0:1], v[0:1]
	v_pk_mov_b32 v[36:37], v[0:1], v[0:1]
	v_pk_mov_b32 v[38:39], v[0:1], v[0:1]
	v_pk_mov_b32 v[40:41], v[0:1], v[0:1]
	v_pk_mov_b32 v[42:43], v[0:1], v[0:1]
	v_pk_mov_b32 v[44:45], v[0:1], v[0:1]
	v_pk_mov_b32 v[46:47], v[0:1], v[0:1]
	v_pk_mov_b32 v[48:49], v[0:1], v[0:1]
	v_pk_mov_b32 v[50:51], v[0:1], v[0:1]
	v_pk_mov_b32 v[52:53], v[0:1], v[0:1]
	v_pk_mov_b32 v[54:55], v[0:1], v[0:1]
	v_pk_mov_b32 v[56:57], v[0:1], v[0:1]
	v_pk_mov_b32 v[58:59], v[0:1], v[0:1]
	v_pk_mov_b32 v[60:61], v[0:1], v[0:1]
	v_pk_mov_b32 v[62:63], v[0:1], v[0:1]
	v_pk_mov_b32 v[64:65], v[0:1], v[0:1]
	v_pk_mov_b32 v[66:67], v[0:1], v[0:1]
	v_pk_mov_b32 v[68:69], v[0:1], v[0:1]
	v_pk_mov_b32 v[70:71], v[0:1], v[0:1]
	v_pk_mov_b32 v[72:73], v[0:1], v[0:1]
	v_pk_mov_b32 v[74:75], v[0:1], v[0:1]
	v_pk_mov_b32 v[76:77], v[0:1], v[0:1]
	v_pk_mov_b32 v[78:79], v[0:1], v[0:1]
	v_pk_mov_b32 v[80:81], v[0:1], v[0:1]
	v_pk_mov_b32 v[82:83], v[0:1], v[0:1]
	v_pk_mov_b32 v[84:85], v[0:1], v[0:1]
	v_pk_mov_b32 v[86:87], v[0:1], v[0:1]
	v_pk_mov_b32 v[88:89], v[0:1], v[0:1]
	v_pk_mov_b32 v[90:91], v[0:1], v[0:1]
	v_pk_mov_b32 v[92:93], v[0:1], v[0:1]
	v_pk_mov_b32 v[94:95], v[0:1], v[0:1]
	v_pk_mov_b32 v[96:97], v[0:1], v[0:1]
	v_pk_mov_b32 v[98:99], v[0:1], v[0:1]
	v_pk_mov_b32 v[100:101], v[0:1], v[0:1]
	v_pk_mov_b32 v[102:103], v[0:1], v[0:1]
	v_pk_mov_b32 v[104:105], v[0:1], v[0:1]
	v_pk_mov_b32 v[106:107], v[0:1], v[0:1]
	v_pk_mov_b32 v[108:109], v[0:1], v[0:1]
	v_pk_mov_b32 v[110:111], v[0:1], v[0:1]
	v_pk_mov_b32 v[112:113], v[0:1], v[0:1]
	v_pk_mov_b32 v[114:115], v[0:1], v[0:1]
	v_pk_mov_b32 v[116:117], v[0:1], v[0:1]
	v_pk_mov_b32 v[118:119], v[0:1], v[0:1]
	v_pk_mov_b32 v[120:121], v[0:1], v[0:1]
	v_pk_mov_b32 v[122:123], v[0:1], v[0:1]
	v_pk_mov_b32 v[124:125], v[0:1], v[0:1]
	v_pk_mov_b32 v[126:127], v[0:1], v[0:1]
	ds_read_b128 v[144:147], v207
	ds_read_b128 v[148:151], v207 offset:1024
	ds_read_b128 v[152:155], v207 offset:2048
	ds_read_b128 v[156:159], v207 offset:3072
; #define PG8_STAGE(bufoff, gbase, voff) do { _Pragma("unroll") for (int _i = 0; _i < 2; ++_i) \
;         __builtin_amdgcn_global_load_lds((const unsigned*)((const char*)(gbase) + (voff)[_i]), (LAS unsigned*)(lds + (bufoff) + ldsw + _i * 8192), 16, 0, 0); } while (0)
; #define PG8_LDA(dst, b, h) do { _Pragma("unroll") for (int m = 0; m < 4; ++m) _Pragma("unroll") for (int k = 0; k < 2; ++k) dst[m][k] = *(const LAS bf16x8*)(lds + PG8_SA(b, h) + aoff + m * 2048 + k * 1024); } while (0)
; #define PG8_LDB(dst, b, h) do { _Pragma("unroll") for (int n = 0; n < 2; ++n) _Pragma("unroll") for (int k = 0; k < 2; ++k) dst[n][k] = *(const LAS bf16x8*)(lds + PG8_SB(b, h) + boff + n * 2048 + k * 1024); } while (0)
; #define PG8_MMA(ai, bj, At, Bt) do { __builtin_amdgcn_s_setprio(1); _Pragma("unroll") for (int m = 0; m < 4; ++m) _Pragma("unroll") for (int n = 0; n < 2; ++n) _Pragma("unroll") for (int k = 0; k < 2; ++k) \
;         acc[ai][bj][m][n] = __builtin_amdgcn_mfma_f32_16x16x32_bf16(Bt[n][k], At[m][k], acc[ai][bj][m][n], 0, 0, 0); __builtin_amdgcn_s_setprio(0); } while (0)
; #define PG8_WAIT_V(n) asm volatile("s_waitcnt vmcnt(" #n ")" ::: "memory")
; #define PG8_WAIT_L(n) asm volatile("s_waitcnt lgkmcnt(" #n ")" ::: "memory")
; #define PG8_BAR __builtin_amdgcn_s_barrier()
; #define PG8_SCHED __builtin_amdgcn_sched_barrier(0)
; template <class Epi>
; __device__ __forceinline__ void gemm_phase(LAS unsigned char* lds, const int tid, const Gemm g, const StaticOrder& S, const Epi& E) {
;     ...
;             PG8_LDB(B0, 0, 0); PG8_LDB(B1, 0, 1); PG8_SCHED; PG8_LDA(At, 0, 0); PG8_STAGE(PG8_SA(1, 1), a1 + hstepA, voffA);
;             PG8_WAIT_V(8); PG8_WAIT_L(0); PG8_BAR; PG8_MMA(0, 0, At, B0); PG8_MMA(0, 1, At, B1); PG8_BAR; PG8_SCHED;
;             PG8_LDA(At, 0, 1); PG8_STAGE(PG8_SB(0, 0), b2, voffB); PG8_STAGE(PG8_SB(0, 1), b2 + hstepB, voffB); PG8_STAGE(PG8_SA(0, 0), a2, voffA);
;             PG8_WAIT_V(8); PG8_WAIT_L(0); PG8_BAR; PG8_MMA(1, 0, At, B0); PG8_MMA(1, 1, At, B1); PG8_BAR; PG8_SCHED;
.LBB0_352:
	ds_read_b128 v[160:163], v208
	ds_read_b128 v[164:167], v208 offset:1024
	ds_read_b128 v[168:171], v208 offset:2048
	ds_read_b128 v[172:175], v208 offset:3072
	s_add_i32 s60, s30, 2
	s_add_u32 s28, s26, 0x100
	s_addc_u32 s29, s27, 0
	s_cmp_eq_u32 s49, s30
	s_cselect_b32 s30, s24, s58
	s_cselect_b32 s35, s7, s29
	s_cselect_b32 s34, s6, s28
	s_cselect_b32 s31, s25, s59
	v_lshl_add_u64 v[214:215], s[26:27], 0, v[138:139]
	s_add_i32 m0, s41, 0xc000
	ds_read_b128 v[176:179], v209
	ds_read_b128 v[180:183], v209 offset:1024
	ds_read_b128 v[184:187], v209 offset:2048
	ds_read_b128 v[188:191], v209 offset:3072
	ds_read_b128 v[192:195], v209 offset:4096
	ds_read_b128 v[196:199], v209 offset:5120
	ds_read_b128 v[200:203], v209 offset:6144
	ds_read_b128 v[210:213], v209 offset:7168
	global_load_lds_dwordx4 v[214:215], off
	v_lshl_add_u64 v[214:215], s[26:27], 0, v[136:137]
	s_add_i32 m0, s41, 0xe000
	s_nop 0
	global_load_lds_dwordx4 v[214:215], off
	s_waitcnt vmcnt(6)
	s_waitcnt lgkmcnt(0)
	s_barrier
	s_setprio 1
	v_mfma_f32_16x16x32_bf16 v[124:127], v[144:147], v[176:179], v[124:127]
	v_mfma_f32_16x16x32_bf16 v[120:123], v[152:155], v[176:179], v[120:123]
	v_mfma_f32_16x16x32_bf16 v[116:119], v[144:147], v[184:187], v[116:119]
	v_mfma_f32_16x16x32_bf16 v[112:115], v[152:155], v[184:187], v[112:115]
	v_mfma_f32_16x16x32_bf16 v[104:107], v[144:147], v[192:195], v[104:107]
	v_mfma_f32_16x16x32_bf16 v[96:99], v[152:155], v[192:195], v[96:99]
	v_mfma_f32_16x16x32_bf16 v[88:91], v[144:147], v[200:203], v[88:91]
	v_mfma_f32_16x16x32_bf16 v[80:83], v[152:155], v[200:203], v[80:83]
	v_mfma_f32_16x16x32_bf16 v[124:127], v[148:151], v[180:183], v[124:127]
	v_mfma_f32_16x16x32_bf16 v[120:123], v[156:159], v[180:183], v[120:123]
	v_mfma_f32_16x16x32_bf16 v[116:119], v[148:151], v[188:191], v[116:119]
	v_mfma_f32_16x16x32_bf16 v[112:115], v[156:159], v[188:191], v[112:115]
	v_mfma_f32_16x16x32_bf16 v[104:107], v[148:151], v[196:199], v[104:107]
	v_mfma_f32_16x16x32_bf16 v[96:99], v[156:159], v[196:199], v[96:99]
	v_mfma_f32_16x16x32_bf16 v[88:91], v[148:151], v[210:213], v[88:91]
	v_mfma_f32_16x16x32_bf16 v[80:83], v[156:159], v[210:213], v[80:83]
	v_mfma_f32_16x16x32_bf16 v[108:111], v[160:163], v[176:179], v[108:111]
	v_mfma_f32_16x16x32_bf16 v[100:103], v[168:171], v[176:179], v[100:103]
	v_mfma_f32_16x16x32_bf16 v[92:95], v[160:163], v[184:187], v[92:95]
	v_mfma_f32_16x16x32_bf16 v[84:87], v[168:171], v[184:187], v[84:87]
	v_mfma_f32_16x16x32_bf16 v[76:79], v[160:163], v[192:195], v[76:79]
	v_mfma_f32_16x16x32_bf16 v[72:75], v[168:171], v[192:195], v[72:75]
	v_mfma_f32_16x16x32_bf16 v[68:71], v[160:163], v[200:203], v[68:71]
	v_mfma_f32_16x16x32_bf16 v[64:67], v[168:171], v[200:203], v[64:67]
	v_mfma_f32_16x16x32_bf16 v[108:111], v[164:167], v[180:183], v[108:111]
	v_mfma_f32_16x16x32_bf16 v[100:103], v[172:175], v[180:183], v[100:103]
	v_mfma_f32_16x16x32_bf16 v[92:95], v[164:167], v[188:191], v[92:95]
	v_mfma_f32_16x16x32_bf16 v[84:87], v[172:175], v[188:191], v[84:87]
	v_mfma_f32_16x16x32_bf16 v[76:79], v[164:167], v[196:199], v[76:79]
	v_mfma_f32_16x16x32_bf16 v[72:75], v[172:175], v[196:199], v[72:75]
	v_mfma_f32_16x16x32_bf16 v[68:71], v[164:167], v[210:213], v[68:71]
	v_mfma_f32_16x16x32_bf16 v[64:67], v[172:175], v[210:213], v[64:67]
	s_setprio 0
	s_barrier
	s_add_i32 s26, s52, s40
	v_lshl_add_u64 v[214:215], s[30:31], 0, v[130:131]
	s_mov_b32 m0, s26
	ds_read_b128 v[176:179], v209 offset:16384
	ds_read_b128 v[180:183], v209 offset:17408
	ds_read_b128 v[184:187], v209 offset:18432
	ds_read_b128 v[188:191], v209 offset:19456
	ds_read_b128 v[192:195], v209 offset:20480
	ds_read_b128 v[196:199], v209 offset:21504
	ds_read_b128 v[200:203], v209 offset:22528
	ds_read_b128 v[210:213], v209 offset:23552
	global_load_lds_dwordx4 v[214:215], off
	s_add_i32 m0, s26, 0x2000
	s_add_u32 s26, s30, 0xb0000
	v_lshl_add_u64 v[216:217], s[30:31], 0, v[134:135]
	s_addc_u32 s27, s31, 0
	s_add_i32 s61, s53, s40
	global_load_lds_dwordx4 v[216:217], off
	v_lshl_add_u64 v[218:219], s[26:27], 0, v[130:131]
	s_mov_b32 m0, s61
	v_lshl_add_u64 v[220:221], s[34:35], 0, v[132:133]
	global_load_lds_dwordx4 v[218:219], off
	v_lshl_add_u64 v[218:219], s[26:27], 0, v[134:135]
	s_add_i32 m0, s61, 0x2000
	s_nop 0
	global_load_lds_dwordx4 v[218:219], off
	v_lshl_add_u64 v[218:219], s[34:35], 0, v[128:129]
	s_mov_b32 m0, s41
	s_nop 0
	global_load_lds_dwordx4 v[218:219], off
	s_mov_b32 m0, s42
	s_nop 0
	global_load_lds_dwordx4 v[220:221], off
	s_waitcnt vmcnt(8)
	s_waitcnt lgkmcnt(0)
	s_barrier
; #define PG8_STAGE(bufoff, gbase, voff) do { _Pragma("unroll") for (int _i = 0; _i < 2; ++_i) \
;         __builtin_amdgcn_global_load_lds((const unsigned*)((const char*)(gbase) + (voff)[_i]), (LAS unsigned*)(lds + (bufoff) + ldsw + _i * 8192), 16, 0, 0); } while (0)
; #define PG8_LDA(dst, b, h) do { _Pragma("unroll") for (int m = 0; m < 4; ++m) _Pragma("unroll") for (int k = 0; k < 2; ++k) dst[m][k] = *(const LAS bf16x8*)(lds + PG8_SA(b, h) + aoff + m * 2048 + k * 1024); } while (0)
; #define PG8_LDB(dst, b, h) do { _Pragma("unroll") for (int n = 0; n < 2; ++n) _Pragma("unroll") for (int k = 0; k < 2; ++k) dst[n][k] = *(const LAS bf16x8*)(lds + PG8_SB(b, h) + boff + n * 2048 + k * 1024); } while (0)
; #define PG8_MMA(ai, bj, At, Bt) do { __builtin_amdgcn_s_setprio(1); _Pragma("unroll") for (int m = 0; m < 4; ++m) _Pragma("unroll") for (int n = 0; n < 2; ++n) _Pragma("unroll") for (int k = 0; k < 2; ++k) \
;         acc[ai][bj][m][n] = __builtin_amdgcn_mfma_f32_16x16x32_bf16(Bt[n][k], At[m][k], acc[ai][bj][m][n], 0, 0, 0); __builtin_amdgcn_s_setprio(0); } while (0)
; #define PG8_WAIT_V(n) asm volatile("s_waitcnt vmcnt(" #n ")" ::: "memory")
; #define PG8_WAIT_L(n) asm volatile("s_waitcnt lgkmcnt(" #n ")" ::: "memory")
; #define PG8_BAR __builtin_amdgcn_s_barrier()
; #define PG8_SCHED __builtin_amdgcn_sched_barrier(0)
; template <class Epi>
; __device__ __forceinline__ void gemm_phase(LAS unsigned char* lds, const int tid, const Gemm g, const StaticOrder& S, const Epi& E) {
;     ...
;             PG8_WAIT_V(8); PG8_WAIT_L(0); PG8_BAR; PG8_MMA(1, 0, At, B0); PG8_MMA(1, 1, At, B1); PG8_BAR; PG8_SCHED;
;             PG8_LDB(B0, 1, 0); PG8_LDB(B1, 1, 1); PG8_SCHED; PG8_LDA(At, 1, 0); PG8_STAGE(PG8_SA(0, 1), a2 + hstepA, voffA);
;             PG8_WAIT_V(8); PG8_WAIT_L(0); PG8_BAR; PG8_MMA(0, 0, At, B0); PG8_MMA(0, 1, At, B1); PG8_BAR; PG8_SCHED;
	s_setprio 1
	v_mfma_f32_16x16x32_bf16 v[60:63], v[144:147], v[176:179], v[60:63]
	v_mfma_f32_16x16x32_bf16 v[56:59], v[152:155], v[176:179], v[56:59]
	v_mfma_f32_16x16x32_bf16 v[52:55], v[144:147], v[184:187], v[52:55]
	v_mfma_f32_16x16x32_bf16 v[48:51], v[152:155], v[184:187], v[48:51]
	v_mfma_f32_16x16x32_bf16 v[40:43], v[144:147], v[192:195], v[40:43]
	v_mfma_f32_16x16x32_bf16 v[32:35], v[152:155], v[192:195], v[32:35]
	v_mfma_f32_16x16x32_bf16 v[24:27], v[144:147], v[200:203], v[24:27]
	v_mfma_f32_16x16x32_bf16 v[16:19], v[152:155], v[200:203], v[16:19]
	v_mfma_f32_16x16x32_bf16 v[60:63], v[148:151], v[180:183], v[60:63]
	v_mfma_f32_16x16x32_bf16 v[56:59], v[156:159], v[180:183], v[56:59]
	v_mfma_f32_16x16x32_bf16 v[52:55], v[148:151], v[188:191], v[52:55]
	v_mfma_f32_16x16x32_bf16 v[48:51], v[156:159], v[188:191], v[48:51]
	v_mfma_f32_16x16x32_bf16 v[40:43], v[148:151], v[196:199], v[40:43]
	v_mfma_f32_16x16x32_bf16 v[32:35], v[156:159], v[196:199], v[32:35]
	v_mfma_f32_16x16x32_bf16 v[24:27], v[148:151], v[210:213], v[24:27]
	v_mfma_f32_16x16x32_bf16 v[16:19], v[156:159], v[210:213], v[16:19]
	v_mfma_f32_16x16x32_bf16 v[44:47], v[160:163], v[176:179], v[44:47]
	v_add_u32_e32 v156, 0x18000, v205
	v_mfma_f32_16x16x32_bf16 v[36:39], v[168:171], v[176:179], v[36:39]
	v_mfma_f32_16x16x32_bf16 v[28:31], v[160:163], v[184:187], v[28:31]
	ds_read_b128 v[144:147], v156
	v_mfma_f32_16x16x32_bf16 v[20:23], v[168:171], v[184:187], v[20:23]
	v_mfma_f32_16x16x32_bf16 v[12:15], v[160:163], v[192:195], v[12:15]
	v_mfma_f32_16x16x32_bf16 v[8:11], v[168:171], v[192:195], v[8:11]
	ds_read_b128 v[148:151], v156 offset:1024
	v_mfma_f32_16x16x32_bf16 v[4:7], v[160:163], v[200:203], v[4:7]
	v_mfma_f32_16x16x32_bf16 v[0:3], v[168:171], v[200:203], v[0:3]
	v_mfma_f32_16x16x32_bf16 v[44:47], v[164:167], v[180:183], v[44:47]
	ds_read_b128 v[152:155], v156 offset:2048
	v_mfma_f32_16x16x32_bf16 v[36:39], v[172:175], v[180:183], v[36:39]
	v_mfma_f32_16x16x32_bf16 v[28:31], v[164:167], v[188:191], v[28:31]
	v_mfma_f32_16x16x32_bf16 v[20:23], v[172:175], v[188:191], v[20:23]
	ds_read_b128 v[156:159], v156 offset:3072
	v_mfma_f32_16x16x32_bf16 v[12:15], v[164:167], v[196:199], v[12:15]
	v_mfma_f32_16x16x32_bf16 v[8:11], v[172:175], v[196:199], v[8:11]
	v_mfma_f32_16x16x32_bf16 v[4:7], v[164:167], v[210:213], v[4:7]
	v_mfma_f32_16x16x32_bf16 v[0:3], v[172:175], v[210:213], v[0:3]
	s_setprio 0
	s_barrier
	s_add_i32 s61, 0, 0x18000
	s_add_i32 s62, 0, 0x1c000
	v_add_u32_e32 v172, s62, v205
	ds_read_b128 v[160:163], v172
	ds_read_b128 v[164:167], v172 offset:1024
	ds_read_b128 v[168:171], v172 offset:2048
	ds_read_b128 v[172:175], v172 offset:3072
	s_add_u32 s26, s34, 0xb0000
	s_addc_u32 s27, s35, 0
	s_mov_b32 m0, s43
	v_lshl_add_u64 v[222:223], s[26:27], 0, v[128:129]
	ds_read_b128 v[176:179], v209 offset:32768
	ds_read_b128 v[180:183], v209 offset:33792
	ds_read_b128 v[184:187], v209 offset:34816
	ds_read_b128 v[188:191], v209 offset:35840
	ds_read_b128 v[192:195], v209 offset:36864
	ds_read_b128 v[196:199], v209 offset:37888
	ds_read_b128 v[200:203], v209 offset:38912
	ds_read_b128 v[210:213], v209 offset:39936
	global_load_lds_dwordx4 v[222:223], off
	v_lshl_add_u64 v[222:223], s[26:27], 0, v[132:133]
	s_mov_b32 m0, s44
	s_nop 0
	global_load_lds_dwordx4 v[222:223], off
	s_waitcnt vmcnt(6)
	s_waitcnt lgkmcnt(0)
	s_barrier
	s_setprio 1
	v_mfma_f32_16x16x32_bf16 v[124:127], v[144:147], v[176:179], v[124:127]
	v_mfma_f32_16x16x32_bf16 v[120:123], v[152:155], v[176:179], v[120:123]
	v_mfma_f32_16x16x32_bf16 v[116:119], v[144:147], v[184:187], v[116:119]
	v_mfma_f32_16x16x32_bf16 v[112:115], v[152:155], v[184:187], v[112:115]
	v_mfma_f32_16x16x32_bf16 v[104:107], v[144:147], v[192:195], v[104:107]
	v_mfma_f32_16x16x32_bf16 v[96:99], v[152:155], v[192:195], v[96:99]
	v_mfma_f32_16x16x32_bf16 v[88:91], v[144:147], v[200:203], v[88:91]
	v_mfma_f32_16x16x32_bf16 v[80:83], v[152:155], v[200:203], v[80:83]
	v_mfma_f32_16x16x32_bf16 v[124:127], v[148:151], v[180:183], v[124:127]
	v_mfma_f32_16x16x32_bf16 v[120:123], v[156:159], v[180:183], v[120:123]
	v_mfma_f32_16x16x32_bf16 v[116:119], v[148:151], v[188:191], v[116:119]
	v_mfma_f32_16x16x32_bf16 v[112:115], v[156:159], v[188:191], v[112:115]
	v_mfma_f32_16x16x32_bf16 v[104:107], v[148:151], v[196:199], v[104:107]
	v_mfma_f32_16x16x32_bf16 v[96:99], v[156:159], v[196:199], v[96:99]
	v_mfma_f32_16x16x32_bf16 v[88:91], v[148:151], v[210:213], v[88:91]
	v_mfma_f32_16x16x32_bf16 v[80:83], v[156:159], v[210:213], v[80:83]
	v_mfma_f32_16x16x32_bf16 v[108:111], v[160:163], v[176:179], v[108:111]
	v_mfma_f32_16x16x32_bf16 v[100:103], v[168:171], v[176:179], v[100:103]
	v_mfma_f32_16x16x32_bf16 v[92:95], v[160:163], v[184:187], v[92:95]
	v_mfma_f32_16x16x32_bf16 v[84:87], v[168:171], v[184:187], v[84:87]
	v_mfma_f32_16x16x32_bf16 v[76:79], v[160:163], v[192:195], v[76:79]
	v_mfma_f32_16x16x32_bf16 v[72:75], v[168:171], v[192:195], v[72:75]
	v_mfma_f32_16x16x32_bf16 v[68:71], v[160:163], v[200:203], v[68:71]
	v_mfma_f32_16x16x32_bf16 v[64:67], v[168:171], v[200:203], v[64:67]
	v_mfma_f32_16x16x32_bf16 v[108:111], v[164:167], v[180:183], v[108:111]
	v_mfma_f32_16x16x32_bf16 v[100:103], v[172:175], v[180:183], v[100:103]
	v_mfma_f32_16x16x32_bf16 v[92:95], v[164:167], v[188:191], v[92:95]
	v_mfma_f32_16x16x32_bf16 v[84:87], v[172:175], v[188:191], v[84:87]
	v_mfma_f32_16x16x32_bf16 v[76:79], v[164:167], v[196:199], v[76:79]
	v_mfma_f32_16x16x32_bf16 v[72:75], v[172:175], v[196:199], v[72:75]
	v_mfma_f32_16x16x32_bf16 v[68:71], v[164:167], v[210:213], v[68:71]
	v_mfma_f32_16x16x32_bf16 v[64:67], v[172:175], v[210:213], v[64:67]
	s_setprio 0
	s_barrier
; #define PG8_STAGE(bufoff, gbase, voff) do { _Pragma("unroll") for (int _i = 0; _i < 2; ++_i) \
;         __builtin_amdgcn_global_load_lds((const unsigned*)((const char*)(gbase) + (voff)[_i]), (LAS unsigned*)(lds + (bufoff) + ldsw + _i * 8192), 16, 0, 0); } while (0)
; #define PG8_LDA(dst, b, h) do { _Pragma("unroll") for (int m = 0; m < 4; ++m) _Pragma("unroll") for (int k = 0; k < 2; ++k) dst[m][k] = *(const LAS bf16x8*)(lds + PG8_SA(b, h) + aoff + m * 2048 + k * 1024); } while (0)
; #define PG8_MMA(ai, bj, At, Bt) do { __builtin_amdgcn_s_setprio(1); _Pragma("unroll") for (int m = 0; m < 4; ++m) _Pragma("unroll") for (int n = 0; n < 2; ++n) _Pragma("unroll") for (int k = 0; k < 2; ++k) \
;         acc[ai][bj][m][n] = __builtin_amdgcn_mfma_f32_16x16x32_bf16(Bt[n][k], At[m][k], acc[ai][bj][m][n], 0, 0, 0); __builtin_amdgcn_s_setprio(0); } while (0)
; #define PG8_WAIT_V(n) asm volatile("s_waitcnt vmcnt(" #n ")" ::: "memory")
; #define PG8_WAIT_L(n) asm volatile("s_waitcnt lgkmcnt(" #n ")" ::: "memory")
; #define PG8_BAR __builtin_amdgcn_s_barrier()
; #define PG8_SCHED __builtin_amdgcn_sched_barrier(0)
; template <class Epi>
; __device__ __forceinline__ void gemm_phase(LAS unsigned char* lds, const int tid, const Gemm g, const StaticOrder& S, const Epi& E) {
;     ...
;             PG8_LDA(At, 1, 1); PG8_STAGE(PG8_SB(1, 0), b3, voffB); PG8_STAGE(PG8_SB(1, 1), b3 + hstepB, voffB); PG8_STAGE(PG8_SA(1, 0), a3, voffA);
;             PG8_WAIT_V(8); PG8_WAIT_L(0); PG8_BAR; PG8_MMA(1, 0, At, B0); PG8_MMA(1, 1, At, B1); PG8_BAR; PG8_SCHED;
	s_add_i32 s26, s61, s40
	v_lshl_add_u64 v[214:215], v[214:215], 0, s[18:19]
	s_mov_b32 m0, s26
	ds_read_b128 v[176:179], v209 offset:49152
	ds_read_b128 v[180:183], v209 offset:50176
	ds_read_b128 v[184:187], v209 offset:51200
	ds_read_b128 v[188:191], v209 offset:52224
	ds_read_b128 v[192:195], v209 offset:53248
	ds_read_b128 v[196:199], v209 offset:54272
	ds_read_b128 v[200:203], v209 offset:55296
	ds_read_b128 v[210:213], v209 offset:56320
	global_load_lds_dwordx4 v[214:215], off
	s_add_i32 m0, s26, 0x2000
	s_add_u32 s26, s30, 0xb0080
	v_lshl_add_u64 v[214:215], v[216:217], 0, s[18:19]
	s_addc_u32 s27, s31, 0
	s_add_i32 s30, s62, s40
	global_load_lds_dwordx4 v[214:215], off
	v_lshl_add_u64 v[214:215], s[26:27], 0, v[130:131]
	s_mov_b32 m0, s30
	s_nop 0
	global_load_lds_dwordx4 v[214:215], off
	v_lshl_add_u64 v[214:215], s[26:27], 0, v[134:135]
	s_add_i32 m0, s30, 0x2000
	s_nop 0
	global_load_lds_dwordx4 v[214:215], off
	v_lshl_add_u64 v[214:215], v[218:219], 0, s[18:19]
	s_mov_b32 m0, s47
	s_nop 0
	global_load_lds_dwordx4 v[214:215], off
	v_lshl_add_u64 v[214:215], v[220:221], 0, s[18:19]
	s_mov_b32 m0, s48
	s_nop 0
	global_load_lds_dwordx4 v[214:215], off
	s_waitcnt vmcnt(8)
	s_waitcnt lgkmcnt(0)
	s_barrier
	s_setprio 1
	v_mfma_f32_16x16x32_bf16 v[60:63], v[144:147], v[176:179], v[60:63]
	v_mfma_f32_16x16x32_bf16 v[56:59], v[152:155], v[176:179], v[56:59]
	v_mfma_f32_16x16x32_bf16 v[52:55], v[144:147], v[184:187], v[52:55]
	v_mfma_f32_16x16x32_bf16 v[48:51], v[152:155], v[184:187], v[48:51]
	v_mfma_f32_16x16x32_bf16 v[40:43], v[144:147], v[192:195], v[40:43]
	v_mfma_f32_16x16x32_bf16 v[32:35], v[152:155], v[192:195], v[32:35]
	v_mfma_f32_16x16x32_bf16 v[24:27], v[144:147], v[200:203], v[24:27]
	v_mfma_f32_16x16x32_bf16 v[16:19], v[152:155], v[200:203], v[16:19]
	v_mfma_f32_16x16x32_bf16 v[60:63], v[148:151], v[180:183], v[60:63]
	v_mfma_f32_16x16x32_bf16 v[56:59], v[156:159], v[180:183], v[56:59]
	v_mfma_f32_16x16x32_bf16 v[52:55], v[148:151], v[188:191], v[52:55]
	v_mfma_f32_16x16x32_bf16 v[48:51], v[156:159], v[188:191], v[48:51]
	v_mfma_f32_16x16x32_bf16 v[40:43], v[148:151], v[196:199], v[40:43]
	v_mfma_f32_16x16x32_bf16 v[32:35], v[156:159], v[196:199], v[32:35]
	v_mfma_f32_16x16x32_bf16 v[24:27], v[148:151], v[210:213], v[24:27]
	v_mfma_f32_16x16x32_bf16 v[16:19], v[156:159], v[210:213], v[16:19]
	v_mfma_f32_16x16x32_bf16 v[44:47], v[160:163], v[176:179], v[44:47]
	v_mfma_f32_16x16x32_bf16 v[36:39], v[168:171], v[176:179], v[36:39]
	v_mfma_f32_16x16x32_bf16 v[28:31], v[160:163], v[184:187], v[28:31]
	ds_read_b128 v[144:147], v207
	v_mfma_f32_16x16x32_bf16 v[20:23], v[168:171], v[184:187], v[20:23]
	v_mfma_f32_16x16x32_bf16 v[12:15], v[160:163], v[192:195], v[12:15]
	v_mfma_f32_16x16x32_bf16 v[8:11], v[168:171], v[192:195], v[8:11]
	ds_read_b128 v[148:151], v207 offset:1024
	v_mfma_f32_16x16x32_bf16 v[4:7], v[160:163], v[200:203], v[4:7]
	v_mfma_f32_16x16x32_bf16 v[0:3], v[168:171], v[200:203], v[0:3]
	v_mfma_f32_16x16x32_bf16 v[44:47], v[164:167], v[180:183], v[44:47]
	ds_read_b128 v[152:155], v207 offset:2048
	v_mfma_f32_16x16x32_bf16 v[36:39], v[172:175], v[180:183], v[36:39]
	v_mfma_f32_16x16x32_bf16 v[28:31], v[164:167], v[188:191], v[28:31]
	v_mfma_f32_16x16x32_bf16 v[20:23], v[172:175], v[188:191], v[20:23]
	ds_read_b128 v[156:159], v207 offset:3072
	v_mfma_f32_16x16x32_bf16 v[12:15], v[164:167], v[196:199], v[12:15]
	v_mfma_f32_16x16x32_bf16 v[8:11], v[172:175], v[196:199], v[8:11]
	v_mfma_f32_16x16x32_bf16 v[4:7], v[164:167], v[210:213], v[4:7]
	v_mfma_f32_16x16x32_bf16 v[0:3], v[172:175], v[210:213], v[0:3]
	s_setprio 0
	s_barrier
; #define PG8_BAR __builtin_amdgcn_s_barrier()
; template <class Epi>
; __device__ __forceinline__ void gemm_phase(LAS unsigned char* lds, const int tid, const Gemm g, const StaticOrder& S, const Epi& E) {
;     ...
;         for (int t = 0; t < nt; t += 2) {
;     ...
;         }
;         if (wr == 0) PG8_BAR;
;         E(acc, cur, wr, wc, fr, fq);
;     __device__ __forceinline__ void operator()(const Acc& acc, const Unit& u, int wr, int wc, int fr, int fq) const {
;     ...
;                     const f32x4 h0 = hv[m][bj][0] + acc[ai][bj][m][0] * scale, h1 = hv[m][bj][1] + acc[ai][bj][m][1] * scale;
	s_add_u32 s58, s58, 0x100
	s_addc_u32 s59, s59, 0
	s_cmp_ge_i32 s60, s46
	s_mov_b64 s[26:27], s[28:29]
	s_mov_b32 s30, s60
	s_cbranch_scc0 .LBB0_352
	s_waitcnt lgkmcnt(0)
	v_pk_mul_f32 v[178:179], v[126:127], 0.5 op_sel_hi:[1,0]
	v_pk_mul_f32 v[180:181], v[124:125], 0.5 op_sel_hi:[1,0]
	v_pk_mul_f32 v[182:183], v[122:123], 0.5 op_sel_hi:[1,0]
	v_pk_mul_f32 v[184:185], v[120:121], 0.5 op_sel_hi:[1,0]
	v_pk_mul_f32 v[192:193], v[110:111], 0.5 op_sel_hi:[1,0]
	v_pk_mul_f32 v[190:191], v[108:109], 0.5 op_sel_hi:[1,0]
	v_pk_mul_f32 v[188:189], v[102:103], 0.5 op_sel_hi:[1,0]
	v_pk_mul_f32 v[186:187], v[100:101], 0.5 op_sel_hi:[1,0]
	v_pk_mul_f32 v[176:177], v[118:119], 0.5 op_sel_hi:[1,0]
	v_pk_mul_f32 v[174:175], v[116:117], 0.5 op_sel_hi:[1,0]
	v_pk_mul_f32 v[172:173], v[114:115], 0.5 op_sel_hi:[1,0]
	v_pk_mul_f32 v[170:171], v[112:113], 0.5 op_sel_hi:[1,0]
	v_pk_mul_f32 v[168:169], v[94:95], 0.5 op_sel_hi:[1,0]
	v_pk_mul_f32 v[166:167], v[92:93], 0.5 op_sel_hi:[1,0]
	v_pk_mul_f32 v[164:165], v[86:87], 0.5 op_sel_hi:[1,0]
	v_pk_mul_f32 v[162:163], v[84:85], 0.5 op_sel_hi:[1,0]
	v_pk_mul_f32 v[160:161], v[106:107], 0.5 op_sel_hi:[1,0]
	v_pk_mul_f32 v[158:159], v[104:105], 0.5 op_sel_hi:[1,0]
	v_pk_mul_f32 v[156:157], v[98:99], 0.5 op_sel_hi:[1,0]
	v_pk_mul_f32 v[154:155], v[96:97], 0.5 op_sel_hi:[1,0]
	v_pk_mul_f32 v[152:153], v[78:79], 0.5 op_sel_hi:[1,0]
	v_pk_mul_f32 v[150:151], v[76:77], 0.5 op_sel_hi:[1,0]
	v_pk_mul_f32 v[148:149], v[74:75], 0.5 op_sel_hi:[1,0]
	v_pk_mul_f32 v[146:147], v[72:73], 0.5 op_sel_hi:[1,0]
	v_pk_mul_f32 v[144:145], v[90:91], 0.5 op_sel_hi:[1,0]
	v_pk_mul_f32 v[126:127], v[88:89], 0.5 op_sel_hi:[1,0]
	v_pk_mul_f32 v[124:125], v[82:83], 0.5 op_sel_hi:[1,0]
	v_pk_mul_f32 v[122:123], v[80:81], 0.5 op_sel_hi:[1,0]
	v_pk_mul_f32 v[120:121], v[70:71], 0.5 op_sel_hi:[1,0]
	v_pk_mul_f32 v[118:119], v[68:69], 0.5 op_sel_hi:[1,0]
	v_pk_mul_f32 v[116:117], v[66:67], 0.5 op_sel_hi:[1,0]
	v_pk_mul_f32 v[114:115], v[64:65], 0.5 op_sel_hi:[1,0]
	v_pk_mul_f32 v[96:97], v[62:63], 0.5 op_sel_hi:[1,0]
	v_pk_mul_f32 v[98:99], v[60:61], 0.5 op_sel_hi:[1,0]
	v_pk_mul_f32 v[100:101], v[58:59], 0.5 op_sel_hi:[1,0]
	v_pk_mul_f32 v[102:103], v[56:57], 0.5 op_sel_hi:[1,0]
	v_pk_mul_f32 v[110:111], v[46:47], 0.5 op_sel_hi:[1,0]
	v_pk_mul_f32 v[108:109], v[44:45], 0.5 op_sel_hi:[1,0]
	v_pk_mul_f32 v[106:107], v[38:39], 0.5 op_sel_hi:[1,0]
	v_pk_mul_f32 v[104:105], v[36:37], 0.5 op_sel_hi:[1,0]
	v_pk_mul_f32 v[94:95], v[54:55], 0.5 op_sel_hi:[1,0]
	v_pk_mul_f32 v[92:93], v[52:53], 0.5 op_sel_hi:[1,0]
	v_pk_mul_f32 v[90:91], v[50:51], 0.5 op_sel_hi:[1,0]
	v_pk_mul_f32 v[88:89], v[48:49], 0.5 op_sel_hi:[1,0]
	v_pk_mul_f32 v[86:87], v[30:31], 0.5 op_sel_hi:[1,0]
	v_pk_mul_f32 v[84:85], v[28:29], 0.5 op_sel_hi:[1,0]
	v_pk_mul_f32 v[82:83], v[22:23], 0.5 op_sel_hi:[1,0]
	v_pk_mul_f32 v[80:81], v[20:21], 0.5 op_sel_hi:[1,0]
	v_pk_mul_f32 v[78:79], v[42:43], 0.5 op_sel_hi:[1,0]
	v_pk_mul_f32 v[76:77], v[40:41], 0.5 op_sel_hi:[1,0]
	v_pk_mul_f32 v[74:75], v[34:35], 0.5 op_sel_hi:[1,0]
	v_pk_mul_f32 v[72:73], v[32:33], 0.5 op_sel_hi:[1,0]
	v_pk_mul_f32 v[70:71], v[14:15], 0.5 op_sel_hi:[1,0]
	v_pk_mul_f32 v[68:69], v[12:13], 0.5 op_sel_hi:[1,0]
	v_pk_mul_f32 v[66:67], v[10:11], 0.5 op_sel_hi:[1,0]
	v_pk_mul_f32 v[64:65], v[8:9], 0.5 op_sel_hi:[1,0]
	v_pk_mul_f32 v[62:63], v[26:27], 0.5 op_sel_hi:[1,0]
	v_pk_mul_f32 v[60:61], v[24:25], 0.5 op_sel_hi:[1,0]
	v_pk_mul_f32 v[58:59], v[18:19], 0.5 op_sel_hi:[1,0]
	v_pk_mul_f32 v[56:57], v[16:17], 0.5 op_sel_hi:[1,0]
	v_pk_mul_f32 v[54:55], v[6:7], 0.5 op_sel_hi:[1,0]
	v_pk_mul_f32 v[52:53], v[4:5], 0.5 op_sel_hi:[1,0]
	v_pk_mul_f32 v[50:51], v[2:3], 0.5 op_sel_hi:[1,0]
	v_pk_mul_f32 v[48:49], v[0:1], 0.5 op_sel_hi:[1,0]

; #define PG8_STAGE(bufoff, gbase, voff) do { _Pragma("unroll") for (int _i = 0; _i < 2; ++_i) \
;         __builtin_amdgcn_global_load_lds((const unsigned*)((const char*)(gbase) + (voff)[_i]), (LAS unsigned*)(lds + (bufoff) + ldsw + _i * 8192), 16, 0, 0); } while (0)
; #define PG8_LDA(dst, b, h) do { _Pragma("unroll") for (int m = 0; m < 4; ++m) _Pragma("unroll") for (int k = 0; k < 2; ++k) dst[m][k] = *(const LAS bf16x8*)(lds + PG8_SA(b, h) + aoff + m * 2048 + k * 1024); } while (0)
; #define PG8_LDB(dst, b, h) do { _Pragma("unroll") for (int n = 0; n < 2; ++n) _Pragma("unroll") for (int k = 0; k < 2; ++k) dst[n][k] = *(const LAS bf16x8*)(lds + PG8_SB(b, h) + boff + n * 2048 + k * 1024); } while (0)
; #define PG8_SCHED __builtin_amdgcn_sched_barrier(0)
; template <class Epi>
; __device__ __forceinline__ void gemm_phase(LAS unsigned char* lds, const int tid, const Gemm g, const StaticOrder& S, const Epi& E) {
;     ...
;     f32x4 acc[2][2][4][2];
; #pragma unroll
;     for (int a = 0; a < 2; ++a)
; #pragma unroll
;         for (int b = 0; b < 2; ++b)
; #pragma unroll
;             for (int m = 0; m < 4; ++m)
; #pragma unroll
;                 for (int n = 0; n < 2; ++n) acc[a][b][m][n] = (f32x4){0.f, 0.f, 0.f, 0.f};
;     ...
;             PG8_LDB(B0, 0, 0); PG8_LDB(B1, 0, 1); PG8_SCHED; PG8_LDA(At, 0, 0); PG8_STAGE(PG8_SA(1, 1), a1 + hstepA, voffA);
.LBB0_904:
	v_mov_b32_e32 v155, 0
	s_andn2_b64 vcc, exec, s[18:19]
	v_mov_b32_e32 v154, 0
	v_mov_b32_e32 v157, 0
	v_mov_b32_e32 v156, 0
	v_mov_b32_e32 v159, 0
	v_mov_b32_e32 v158, 0
	v_mov_b32_e32 v161, 0
	v_mov_b32_e32 v160, 0
	v_mov_b32_e32 v153, 0
	v_mov_b32_e32 v152, 0
	v_mov_b32_e32 v151, 0
	v_mov_b32_e32 v150, 0
	v_mov_b32_e32 v149, 0
	v_mov_b32_e32 v148, 0
	v_mov_b32_e32 v147, 0
	v_mov_b32_e32 v146, 0
	v_mov_b32_e32 v121, 0
	v_mov_b32_e32 v120, 0
	v_mov_b32_e32 v119, 0
	v_mov_b32_e32 v118, 0
	v_mov_b32_e32 v117, 0
	v_mov_b32_e32 v116, 0
	v_mov_b32_e32 v115, 0
	v_mov_b32_e32 v114, 0
	v_mov_b32_e32 v105, 0
	v_mov_b32_e32 v104, 0
	v_mov_b32_e32 v103, 0
	v_mov_b32_e32 v102, 0
	v_mov_b32_e32 v101, 0
	v_mov_b32_e32 v100, 0
	v_mov_b32_e32 v99, 0
	v_mov_b32_e32 v98, 0
	v_mov_b32_e32 v169, 0
	v_mov_b32_e32 v168, 0
	v_mov_b32_e32 v167, 0
	v_mov_b32_e32 v166, 0
	v_mov_b32_e32 v165, 0
	v_mov_b32_e32 v164, 0
	v_mov_b32_e32 v163, 0
	v_mov_b32_e32 v162, 0
	v_mov_b32_e32 v145, 0
	v_mov_b32_e32 v144, 0
	v_mov_b32_e32 v127, 0
	v_mov_b32_e32 v126, 0
	v_mov_b32_e32 v125, 0
	v_mov_b32_e32 v124, 0
	v_mov_b32_e32 v123, 0
	v_mov_b32_e32 v122, 0
	v_mov_b32_e32 v113, 0
	v_mov_b32_e32 v112, 0
	v_mov_b32_e32 v111, 0
	v_mov_b32_e32 v110, 0
	v_mov_b32_e32 v109, 0
	v_mov_b32_e32 v108, 0
	v_mov_b32_e32 v107, 0
	v_mov_b32_e32 v106, 0
	v_mov_b32_e32 v97, 0
	v_mov_b32_e32 v96, 0
	v_mov_b32_e32 v95, 0
	v_mov_b32_e32 v94, 0
	v_mov_b32_e32 v93, 0
	v_mov_b32_e32 v92, 0
	v_mov_b32_e32 v91, 0
	v_mov_b32_e32 v90, 0
	v_mov_b32_e32 v73, 0
	v_mov_b32_e32 v72, 0
	v_mov_b32_e32 v75, 0
	v_mov_b32_e32 v74, 0
	v_mov_b32_e32 v77, 0
	v_mov_b32_e32 v76, 0
	v_mov_b32_e32 v79, 0
	v_mov_b32_e32 v78, 0
	v_mov_b32_e32 v71, 0
	v_mov_b32_e32 v70, 0
	v_mov_b32_e32 v69, 0
	v_mov_b32_e32 v68, 0
	v_mov_b32_e32 v67, 0
	v_mov_b32_e32 v66, 0
	v_mov_b32_e32 v65, 0
	v_mov_b32_e32 v64, 0
	v_mov_b32_e32 v55, 0
	v_mov_b32_e32 v54, 0
	v_mov_b32_e32 v53, 0
	v_mov_b32_e32 v52, 0
	v_mov_b32_e32 v51, 0
	v_mov_b32_e32 v50, 0
	v_mov_b32_e32 v49, 0
	v_mov_b32_e32 v48, 0
	v_mov_b32_e32 v39, 0
	v_mov_b32_e32 v38, 0
	v_mov_b32_e32 v37, 0
	v_mov_b32_e32 v36, 0
	v_mov_b32_e32 v35, 0
	v_mov_b32_e32 v34, 0
	v_mov_b32_e32 v33, 0
	v_mov_b32_e32 v32, 0
	v_mov_b32_e32 v87, 0
	v_mov_b32_e32 v86, 0
	v_mov_b32_e32 v85, 0
	v_mov_b32_e32 v84, 0
	v_mov_b32_e32 v83, 0
	v_mov_b32_e32 v82, 0
	v_mov_b32_e32 v81, 0
	v_mov_b32_e32 v80, 0
	v_mov_b32_e32 v63, 0
	v_mov_b32_e32 v62, 0
	v_mov_b32_e32 v61, 0
	v_mov_b32_e32 v60, 0
	v_mov_b32_e32 v59, 0
	v_mov_b32_e32 v58, 0
	v_mov_b32_e32 v57, 0
	v_mov_b32_e32 v56, 0
	v_mov_b32_e32 v47, 0
	v_mov_b32_e32 v46, 0
	v_mov_b32_e32 v45, 0
	v_mov_b32_e32 v44, 0
	v_mov_b32_e32 v43, 0
	v_mov_b32_e32 v42, 0
	v_mov_b32_e32 v41, 0
	v_mov_b32_e32 v40, 0
	v_mov_b32_e32 v31, 0
	v_mov_b32_e32 v30, 0
	v_mov_b32_e32 v29, 0
	v_mov_b32_e32 v28, 0
	v_mov_b32_e32 v27, 0
	v_mov_b32_e32 v26, 0
	v_mov_b32_e32 v25, 0
	v_mov_b32_e32 v24, 0
	s_cbranch_vccnz .LBB0_908
	s_add_u32 s56, s26, 0x100
	v_mov_b32_e32 v0, 0
	v_mov_b32_e32 v1, 0
	s_addc_u32 s57, s27, 0
	s_mov_b32 s28, 0
	v_pk_mov_b32 v[2:3], v[0:1], v[0:1]
	v_pk_mov_b32 v[4:5], v[0:1], v[0:1]
	v_pk_mov_b32 v[6:7], v[0:1], v[0:1]
	v_pk_mov_b32 v[8:9], v[0:1], v[0:1]
	v_pk_mov_b32 v[10:11], v[0:1], v[0:1]
	v_pk_mov_b32 v[12:13], v[0:1], v[0:1]
	v_pk_mov_b32 v[14:15], v[0:1], v[0:1]
	v_pk_mov_b32 v[16:17], v[0:1], v[0:1]
	v_pk_mov_b32 v[18:19], v[0:1], v[0:1]
	v_pk_mov_b32 v[20:21], v[0:1], v[0:1]
	v_pk_mov_b32 v[22:23], v[0:1], v[0:1]
	v_pk_mov_b32 v[24:25], v[0:1], v[0:1]
	v_pk_mov_b32 v[26:27], v[0:1], v[0:1]
	v_pk_mov_b32 v[28:29], v[0:1], v[0:1]
	v_pk_mov_b32 v[30:31], v[0:1], v[0:1]
	v_pk_mov_b32 v[32:33], v[0:1], v[0:1]
	v_pk_mov_b32 v[34:35], v[0:1], v[0:1]
	v_pk_mov_b32 v[36:37], v[0:1], v[0:1]
	v_pk_mov_b32 v[38:39], v[0:1], v[0:1]
	v_pk_mov_b32 v[40:41], v[0:1], v[0:1]
	v_pk_mov_b32 v[42:43], v[0:1], v[0:1]
	v_pk_mov_b32 v[44:45], v[0:1], v[0:1]
	v_pk_mov_b32 v[46:47], v[0:1], v[0:1]
	v_pk_mov_b32 v[48:49], v[0:1], v[0:1]
	v_pk_mov_b32 v[50:51], v[0:1], v[0:1]
	v_pk_mov_b32 v[52:53], v[0:1], v[0:1]
	v_pk_mov_b32 v[54:55], v[0:1], v[0:1]
	v_pk_mov_b32 v[56:57], v[0:1], v[0:1]
	v_pk_mov_b32 v[58:59], v[0:1], v[0:1]
	v_pk_mov_b32 v[60:61], v[0:1], v[0:1]
	v_pk_mov_b32 v[62:63], v[0:1], v[0:1]
	v_pk_mov_b32 v[64:65], v[0:1], v[0:1]
	v_pk_mov_b32 v[66:67], v[0:1], v[0:1]
	v_pk_mov_b32 v[68:69], v[0:1], v[0:1]
	v_pk_mov_b32 v[70:71], v[0:1], v[0:1]
	v_pk_mov_b32 v[72:73], v[0:1], v[0:1]
	v_pk_mov_b32 v[74:75], v[0:1], v[0:1]
	v_pk_mov_b32 v[76:77], v[0:1], v[0:1]
	v_pk_mov_b32 v[78:79], v[0:1], v[0:1]
	v_pk_mov_b32 v[80:81], v[0:1], v[0:1]
	v_pk_mov_b32 v[82:83], v[0:1], v[0:1]
	v_pk_mov_b32 v[84:85], v[0:1], v[0:1]
	v_pk_mov_b32 v[86:87], v[0:1], v[0:1]
	v_pk_mov_b32 v[88:89], v[0:1], v[0:1]
	v_pk_mov_b32 v[90:91], v[0:1], v[0:1]
	v_pk_mov_b32 v[92:93], v[0:1], v[0:1]
	v_pk_mov_b32 v[94:95], v[0:1], v[0:1]
	v_pk_mov_b32 v[96:97], v[0:1], v[0:1]
	v_pk_mov_b32 v[98:99], v[0:1], v[0:1]
	v_pk_mov_b32 v[100:101], v[0:1], v[0:1]
	v_pk_mov_b32 v[102:103], v[0:1], v[0:1]
	v_pk_mov_b32 v[104:105], v[0:1], v[0:1]
	v_pk_mov_b32 v[106:107], v[0:1], v[0:1]
	v_pk_mov_b32 v[108:109], v[0:1], v[0:1]
	v_pk_mov_b32 v[110:111], v[0:1], v[0:1]
	v_pk_mov_b32 v[112:113], v[0:1], v[0:1]
	v_pk_mov_b32 v[114:115], v[0:1], v[0:1]
	v_pk_mov_b32 v[116:117], v[0:1], v[0:1]
	v_pk_mov_b32 v[118:119], v[0:1], v[0:1]
	v_pk_mov_b32 v[120:121], v[0:1], v[0:1]
	v_pk_mov_b32 v[122:123], v[0:1], v[0:1]
	v_pk_mov_b32 v[124:125], v[0:1], v[0:1]
	v_pk_mov_b32 v[126:127], v[0:1], v[0:1]
	ds_read_b128 v[144:147], v189
	ds_read_b128 v[148:151], v189 offset:1024
	ds_read_b128 v[152:155], v189 offset:2048
	ds_read_b128 v[156:159], v189 offset:3072
; #define PG8_STAGE(bufoff, gbase, voff) do { _Pragma("unroll") for (int _i = 0; _i < 2; ++_i) \
;         __builtin_amdgcn_global_load_lds((const unsigned*)((const char*)(gbase) + (voff)[_i]), (LAS unsigned*)(lds + (bufoff) + ldsw + _i * 8192), 16, 0, 0); } while (0)
; #define PG8_LDA(dst, b, h) do { _Pragma("unroll") for (int m = 0; m < 4; ++m) _Pragma("unroll") for (int k = 0; k < 2; ++k) dst[m][k] = *(const LAS bf16x8*)(lds + PG8_SA(b, h) + aoff + m * 2048 + k * 1024); } while (0)
; #define PG8_LDB(dst, b, h) do { _Pragma("unroll") for (int n = 0; n < 2; ++n) _Pragma("unroll") for (int k = 0; k < 2; ++k) dst[n][k] = *(const LAS bf16x8*)(lds + PG8_SB(b, h) + boff + n * 2048 + k * 1024); } while (0)
; #define PG8_MMA(ai, bj, At, Bt) do { __builtin_amdgcn_s_setprio(1); _Pragma("unroll") for (int m = 0; m < 4; ++m) _Pragma("unroll") for (int n = 0; n < 2; ++n) _Pragma("unroll") for (int k = 0; k < 2; ++k) \
;         acc[ai][bj][m][n] = __builtin_amdgcn_mfma_f32_16x16x32_bf16(Bt[n][k], At[m][k], acc[ai][bj][m][n], 0, 0, 0); __builtin_amdgcn_s_setprio(0); } while (0)
; #define PG8_WAIT_V(n) asm volatile("s_waitcnt vmcnt(" #n ")" ::: "memory")
; #define PG8_WAIT_L(n) asm volatile("s_waitcnt lgkmcnt(" #n ")" ::: "memory")
; #define PG8_BAR __builtin_amdgcn_s_barrier()
; #define PG8_SCHED __builtin_amdgcn_sched_barrier(0)
; template <class Epi>
; __device__ __forceinline__ void gemm_phase(LAS unsigned char* lds, const int tid, const Gemm g, const StaticOrder& S, const Epi& E) {
;     ...
;             PG8_LDB(B0, 0, 0); PG8_LDB(B1, 0, 1); PG8_SCHED; PG8_LDA(At, 0, 0); PG8_STAGE(PG8_SA(1, 1), a1 + hstepA, voffA);
;             PG8_WAIT_V(8); PG8_WAIT_L(0); PG8_BAR; PG8_MMA(0, 0, At, B0); PG8_MMA(0, 1, At, B1); PG8_BAR; PG8_SCHED;
;             PG8_LDA(At, 0, 1); PG8_STAGE(PG8_SB(0, 0), b2, voffB); PG8_STAGE(PG8_SB(0, 1), b2 + hstepB, voffB); PG8_STAGE(PG8_SA(0, 0), a2, voffA);
;             PG8_WAIT_V(8); PG8_WAIT_L(0); PG8_BAR; PG8_MMA(1, 0, At, B0); PG8_MMA(1, 1, At, B1); PG8_BAR; PG8_SCHED;
.LBB0_906:
	ds_read_b128 v[160:163], v190
	ds_read_b128 v[164:167], v190 offset:1024
	ds_read_b128 v[168:171], v190 offset:2048
	ds_read_b128 v[172:175], v190 offset:3072
	s_add_i32 s58, s28, 2
	s_add_u32 s26, s24, 0x100
	s_addc_u32 s27, s25, 0
	s_cmp_eq_u32 s47, s28
	s_cselect_b32 s28, s22, s56
	s_cselect_b32 s31, s7, s27
	s_cselect_b32 s30, s6, s26
	s_cselect_b32 s29, s23, s57
	v_lshl_add_u64 v[184:185], s[24:25], 0, v[138:139]
	s_add_i32 m0, s39, 0xc000
	ds_read_b128 v[176:179], v191
	ds_read_b128 v[180:183], v191 offset:1024
	ds_read_b128 v[192:195], v191 offset:2048
	ds_read_b128 v[196:199], v191 offset:3072
	ds_read_b128 v[200:203], v191 offset:4096
	ds_read_b128 v[204:207], v191 offset:5120
	ds_read_b128 v[208:211], v191 offset:6144
	ds_read_b128 v[212:215], v191 offset:7168
	global_load_lds_dwordx4 v[184:185], off
	v_lshl_add_u64 v[184:185], s[24:25], 0, v[136:137]
	s_add_i32 m0, s39, 0xe000
	s_nop 0
	global_load_lds_dwordx4 v[184:185], off
	s_waitcnt vmcnt(6)
	s_waitcnt lgkmcnt(0)
	s_barrier
	s_setprio 1
	v_mfma_f32_16x16x32_bf16 v[124:127], v[144:147], v[176:179], v[124:127]
	v_mfma_f32_16x16x32_bf16 v[120:123], v[152:155], v[176:179], v[120:123]
	v_mfma_f32_16x16x32_bf16 v[116:119], v[144:147], v[192:195], v[116:119]
	v_mfma_f32_16x16x32_bf16 v[112:115], v[152:155], v[192:195], v[112:115]
	v_mfma_f32_16x16x32_bf16 v[104:107], v[144:147], v[200:203], v[104:107]
	v_mfma_f32_16x16x32_bf16 v[96:99], v[152:155], v[200:203], v[96:99]
	v_mfma_f32_16x16x32_bf16 v[88:91], v[144:147], v[208:211], v[88:91]
	v_mfma_f32_16x16x32_bf16 v[80:83], v[152:155], v[208:211], v[80:83]
	v_mfma_f32_16x16x32_bf16 v[124:127], v[148:151], v[180:183], v[124:127]
	v_mfma_f32_16x16x32_bf16 v[120:123], v[156:159], v[180:183], v[120:123]
	v_mfma_f32_16x16x32_bf16 v[116:119], v[148:151], v[196:199], v[116:119]
	v_mfma_f32_16x16x32_bf16 v[112:115], v[156:159], v[196:199], v[112:115]
	v_mfma_f32_16x16x32_bf16 v[104:107], v[148:151], v[204:207], v[104:107]
	v_mfma_f32_16x16x32_bf16 v[96:99], v[156:159], v[204:207], v[96:99]
	v_mfma_f32_16x16x32_bf16 v[88:91], v[148:151], v[212:215], v[88:91]
	v_mfma_f32_16x16x32_bf16 v[80:83], v[156:159], v[212:215], v[80:83]
	v_mfma_f32_16x16x32_bf16 v[108:111], v[160:163], v[176:179], v[108:111]
	v_mfma_f32_16x16x32_bf16 v[100:103], v[168:171], v[176:179], v[100:103]
	v_mfma_f32_16x16x32_bf16 v[92:95], v[160:163], v[192:195], v[92:95]
	v_mfma_f32_16x16x32_bf16 v[84:87], v[168:171], v[192:195], v[84:87]
	v_mfma_f32_16x16x32_bf16 v[76:79], v[160:163], v[200:203], v[76:79]
	v_mfma_f32_16x16x32_bf16 v[72:75], v[168:171], v[200:203], v[72:75]
	v_mfma_f32_16x16x32_bf16 v[68:71], v[160:163], v[208:211], v[68:71]
	v_mfma_f32_16x16x32_bf16 v[64:67], v[168:171], v[208:211], v[64:67]
	v_mfma_f32_16x16x32_bf16 v[108:111], v[164:167], v[180:183], v[108:111]
	v_mfma_f32_16x16x32_bf16 v[100:103], v[172:175], v[180:183], v[100:103]
	v_mfma_f32_16x16x32_bf16 v[92:95], v[164:167], v[196:199], v[92:95]
	v_mfma_f32_16x16x32_bf16 v[84:87], v[172:175], v[196:199], v[84:87]
	v_mfma_f32_16x16x32_bf16 v[76:79], v[164:167], v[204:207], v[76:79]
	v_mfma_f32_16x16x32_bf16 v[72:75], v[172:175], v[204:207], v[72:75]
	v_mfma_f32_16x16x32_bf16 v[68:71], v[164:167], v[212:215], v[68:71]
	v_mfma_f32_16x16x32_bf16 v[64:67], v[172:175], v[212:215], v[64:67]
	s_setprio 0
	s_barrier
	s_add_i32 s24, s50, s38
	v_lshl_add_u64 v[184:185], s[28:29], 0, v[130:131]
	s_mov_b32 m0, s24
	ds_read_b128 v[176:179], v191 offset:16384
	ds_read_b128 v[180:183], v191 offset:17408
	ds_read_b128 v[192:195], v191 offset:18432
	ds_read_b128 v[196:199], v191 offset:19456
	ds_read_b128 v[200:203], v191 offset:20480
	ds_read_b128 v[204:207], v191 offset:21504
	ds_read_b128 v[208:211], v191 offset:22528
	ds_read_b128 v[212:215], v191 offset:23552
	global_load_lds_dwordx4 v[184:185], off
	s_add_i32 m0, s24, 0x2000
	s_add_u32 s24, s28, 0xb0000
	v_lshl_add_u64 v[216:217], s[28:29], 0, v[134:135]
	s_addc_u32 s25, s29, 0
	s_add_i32 s59, s51, s38
	global_load_lds_dwordx4 v[216:217], off
	v_lshl_add_u64 v[218:219], s[24:25], 0, v[130:131]
	s_mov_b32 m0, s59
	v_lshl_add_u64 v[220:221], s[30:31], 0, v[132:133]
	global_load_lds_dwordx4 v[218:219], off
	v_lshl_add_u64 v[218:219], s[24:25], 0, v[134:135]
	s_add_i32 m0, s59, 0x2000
	s_nop 0
	global_load_lds_dwordx4 v[218:219], off
	v_lshl_add_u64 v[218:219], s[30:31], 0, v[128:129]
	s_mov_b32 m0, s39
	s_nop 0
	global_load_lds_dwordx4 v[218:219], off
	s_mov_b32 m0, s40
	s_nop 0
	global_load_lds_dwordx4 v[220:221], off
	s_waitcnt vmcnt(8)
	s_waitcnt lgkmcnt(0)
	s_barrier
; #define PG8_STAGE(bufoff, gbase, voff) do { _Pragma("unroll") for (int _i = 0; _i < 2; ++_i) \
;         __builtin_amdgcn_global_load_lds((const unsigned*)((const char*)(gbase) + (voff)[_i]), (LAS unsigned*)(lds + (bufoff) + ldsw + _i * 8192), 16, 0, 0); } while (0)
; #define PG8_LDA(dst, b, h) do { _Pragma("unroll") for (int m = 0; m < 4; ++m) _Pragma("unroll") for (int k = 0; k < 2; ++k) dst[m][k] = *(const LAS bf16x8*)(lds + PG8_SA(b, h) + aoff + m * 2048 + k * 1024); } while (0)
; #define PG8_LDB(dst, b, h) do { _Pragma("unroll") for (int n = 0; n < 2; ++n) _Pragma("unroll") for (int k = 0; k < 2; ++k) dst[n][k] = *(const LAS bf16x8*)(lds + PG8_SB(b, h) + boff + n * 2048 + k * 1024); } while (0)
; #define PG8_MMA(ai, bj, At, Bt) do { __builtin_amdgcn_s_setprio(1); _Pragma("unroll") for (int m = 0; m < 4; ++m) _Pragma("unroll") for (int n = 0; n < 2; ++n) _Pragma("unroll") for (int k = 0; k < 2; ++k) \
;         acc[ai][bj][m][n] = __builtin_amdgcn_mfma_f32_16x16x32_bf16(Bt[n][k], At[m][k], acc[ai][bj][m][n], 0, 0, 0); __builtin_amdgcn_s_setprio(0); } while (0)
; #define PG8_WAIT_V(n) asm volatile("s_waitcnt vmcnt(" #n ")" ::: "memory")
; #define PG8_WAIT_L(n) asm volatile("s_waitcnt lgkmcnt(" #n ")" ::: "memory")
; #define PG8_BAR __builtin_amdgcn_s_barrier()
; #define PG8_SCHED __builtin_amdgcn_sched_barrier(0)
; template <class Epi>
; __device__ __forceinline__ void gemm_phase(LAS unsigned char* lds, const int tid, const Gemm g, const StaticOrder& S, const Epi& E) {
;     ...
;             PG8_WAIT_V(8); PG8_WAIT_L(0); PG8_BAR; PG8_MMA(1, 0, At, B0); PG8_MMA(1, 1, At, B1); PG8_BAR; PG8_SCHED;
;             PG8_LDB(B0, 1, 0); PG8_LDB(B1, 1, 1); PG8_SCHED; PG8_LDA(At, 1, 0); PG8_STAGE(PG8_SA(0, 1), a2 + hstepA, voffA);
;             PG8_WAIT_V(8); PG8_WAIT_L(0); PG8_BAR; PG8_MMA(0, 0, At, B0); PG8_MMA(0, 1, At, B1); PG8_BAR; PG8_SCHED;
	s_setprio 1
	v_mfma_f32_16x16x32_bf16 v[60:63], v[144:147], v[176:179], v[60:63]
	v_mfma_f32_16x16x32_bf16 v[56:59], v[152:155], v[176:179], v[56:59]
	v_mfma_f32_16x16x32_bf16 v[52:55], v[144:147], v[192:195], v[52:55]
	v_mfma_f32_16x16x32_bf16 v[48:51], v[152:155], v[192:195], v[48:51]
	v_mfma_f32_16x16x32_bf16 v[40:43], v[144:147], v[200:203], v[40:43]
	v_mfma_f32_16x16x32_bf16 v[32:35], v[152:155], v[200:203], v[32:35]
	v_mfma_f32_16x16x32_bf16 v[24:27], v[144:147], v[208:211], v[24:27]
	v_mfma_f32_16x16x32_bf16 v[16:19], v[152:155], v[208:211], v[16:19]
	v_mfma_f32_16x16x32_bf16 v[60:63], v[148:151], v[180:183], v[60:63]
	v_mfma_f32_16x16x32_bf16 v[56:59], v[156:159], v[180:183], v[56:59]
	v_mfma_f32_16x16x32_bf16 v[52:55], v[148:151], v[196:199], v[52:55]
	v_mfma_f32_16x16x32_bf16 v[48:51], v[156:159], v[196:199], v[48:51]
	v_mfma_f32_16x16x32_bf16 v[40:43], v[148:151], v[204:207], v[40:43]
	v_mfma_f32_16x16x32_bf16 v[32:35], v[156:159], v[204:207], v[32:35]
	v_mfma_f32_16x16x32_bf16 v[24:27], v[148:151], v[212:215], v[24:27]
	v_mfma_f32_16x16x32_bf16 v[16:19], v[156:159], v[212:215], v[16:19]
	v_mfma_f32_16x16x32_bf16 v[44:47], v[160:163], v[176:179], v[44:47]
	v_add_u32_e32 v156, 0x18000, v187
	v_mfma_f32_16x16x32_bf16 v[36:39], v[168:171], v[176:179], v[36:39]
	v_mfma_f32_16x16x32_bf16 v[28:31], v[160:163], v[192:195], v[28:31]
	ds_read_b128 v[144:147], v156
	v_mfma_f32_16x16x32_bf16 v[20:23], v[168:171], v[192:195], v[20:23]
	v_mfma_f32_16x16x32_bf16 v[12:15], v[160:163], v[200:203], v[12:15]
	v_mfma_f32_16x16x32_bf16 v[8:11], v[168:171], v[200:203], v[8:11]
	ds_read_b128 v[148:151], v156 offset:1024
	v_mfma_f32_16x16x32_bf16 v[4:7], v[160:163], v[208:211], v[4:7]
	v_mfma_f32_16x16x32_bf16 v[0:3], v[168:171], v[208:211], v[0:3]
	v_mfma_f32_16x16x32_bf16 v[44:47], v[164:167], v[180:183], v[44:47]
	ds_read_b128 v[152:155], v156 offset:2048
	v_mfma_f32_16x16x32_bf16 v[36:39], v[172:175], v[180:183], v[36:39]
	v_mfma_f32_16x16x32_bf16 v[28:31], v[164:167], v[196:199], v[28:31]
	v_mfma_f32_16x16x32_bf16 v[20:23], v[172:175], v[196:199], v[20:23]
	ds_read_b128 v[156:159], v156 offset:3072
	v_mfma_f32_16x16x32_bf16 v[12:15], v[164:167], v[204:207], v[12:15]
	v_mfma_f32_16x16x32_bf16 v[8:11], v[172:175], v[204:207], v[8:11]
	v_mfma_f32_16x16x32_bf16 v[4:7], v[164:167], v[212:215], v[4:7]
	v_mfma_f32_16x16x32_bf16 v[0:3], v[172:175], v[212:215], v[0:3]
	s_setprio 0
	s_barrier
	s_add_i32 s59, 0, 0x18000
	s_add_i32 s60, 0, 0x1c000
	v_add_u32_e32 v172, s60, v187
	ds_read_b128 v[160:163], v172
	ds_read_b128 v[164:167], v172 offset:1024
	ds_read_b128 v[168:171], v172 offset:2048
	ds_read_b128 v[172:175], v172 offset:3072
	s_add_u32 s24, s30, 0xb0000
	s_addc_u32 s25, s31, 0
	s_mov_b32 m0, s41
	v_lshl_add_u64 v[222:223], s[24:25], 0, v[128:129]
	ds_read_b128 v[176:179], v191 offset:32768
	ds_read_b128 v[180:183], v191 offset:33792
	ds_read_b128 v[192:195], v191 offset:34816
	ds_read_b128 v[196:199], v191 offset:35840
	ds_read_b128 v[200:203], v191 offset:36864
	ds_read_b128 v[204:207], v191 offset:37888
	ds_read_b128 v[208:211], v191 offset:38912
	ds_read_b128 v[212:215], v191 offset:39936
	global_load_lds_dwordx4 v[222:223], off
	v_lshl_add_u64 v[222:223], s[24:25], 0, v[132:133]
	s_mov_b32 m0, s42
	s_nop 0
	global_load_lds_dwordx4 v[222:223], off
	s_waitcnt vmcnt(6)
	s_waitcnt lgkmcnt(0)
	s_barrier
	s_setprio 1
	v_mfma_f32_16x16x32_bf16 v[124:127], v[144:147], v[176:179], v[124:127]
	v_mfma_f32_16x16x32_bf16 v[120:123], v[152:155], v[176:179], v[120:123]
	v_mfma_f32_16x16x32_bf16 v[116:119], v[144:147], v[192:195], v[116:119]
	v_mfma_f32_16x16x32_bf16 v[112:115], v[152:155], v[192:195], v[112:115]
	v_mfma_f32_16x16x32_bf16 v[104:107], v[144:147], v[200:203], v[104:107]
	v_mfma_f32_16x16x32_bf16 v[96:99], v[152:155], v[200:203], v[96:99]
	v_mfma_f32_16x16x32_bf16 v[88:91], v[144:147], v[208:211], v[88:91]
	v_mfma_f32_16x16x32_bf16 v[80:83], v[152:155], v[208:211], v[80:83]
	v_mfma_f32_16x16x32_bf16 v[124:127], v[148:151], v[180:183], v[124:127]
	v_mfma_f32_16x16x32_bf16 v[120:123], v[156:159], v[180:183], v[120:123]
	v_mfma_f32_16x16x32_bf16 v[116:119], v[148:151], v[196:199], v[116:119]
	v_mfma_f32_16x16x32_bf16 v[112:115], v[156:159], v[196:199], v[112:115]
	v_mfma_f32_16x16x32_bf16 v[104:107], v[148:151], v[204:207], v[104:107]
	v_mfma_f32_16x16x32_bf16 v[96:99], v[156:159], v[204:207], v[96:99]
	v_mfma_f32_16x16x32_bf16 v[88:91], v[148:151], v[212:215], v[88:91]
	v_mfma_f32_16x16x32_bf16 v[80:83], v[156:159], v[212:215], v[80:83]
	v_mfma_f32_16x16x32_bf16 v[108:111], v[160:163], v[176:179], v[108:111]
	v_mfma_f32_16x16x32_bf16 v[100:103], v[168:171], v[176:179], v[100:103]
	v_mfma_f32_16x16x32_bf16 v[92:95], v[160:163], v[192:195], v[92:95]
	v_mfma_f32_16x16x32_bf16 v[84:87], v[168:171], v[192:195], v[84:87]
	v_mfma_f32_16x16x32_bf16 v[76:79], v[160:163], v[200:203], v[76:79]
	v_mfma_f32_16x16x32_bf16 v[72:75], v[168:171], v[200:203], v[72:75]
	v_mfma_f32_16x16x32_bf16 v[68:71], v[160:163], v[208:211], v[68:71]
	v_mfma_f32_16x16x32_bf16 v[64:67], v[168:171], v[208:211], v[64:67]
	v_mfma_f32_16x16x32_bf16 v[108:111], v[164:167], v[180:183], v[108:111]
	v_mfma_f32_16x16x32_bf16 v[100:103], v[172:175], v[180:183], v[100:103]
	v_mfma_f32_16x16x32_bf16 v[92:95], v[164:167], v[196:199], v[92:95]
	v_mfma_f32_16x16x32_bf16 v[84:87], v[172:175], v[196:199], v[84:87]
	v_mfma_f32_16x16x32_bf16 v[76:79], v[164:167], v[204:207], v[76:79]
	v_mfma_f32_16x16x32_bf16 v[72:75], v[172:175], v[204:207], v[72:75]
	v_mfma_f32_16x16x32_bf16 v[68:71], v[164:167], v[212:215], v[68:71]
	v_mfma_f32_16x16x32_bf16 v[64:67], v[172:175], v[212:215], v[64:67]
	s_setprio 0
	s_barrier
; #define PG8_STAGE(bufoff, gbase, voff) do { _Pragma("unroll") for (int _i = 0; _i < 2; ++_i) \
;         __builtin_amdgcn_global_load_lds((const unsigned*)((const char*)(gbase) + (voff)[_i]), (LAS unsigned*)(lds + (bufoff) + ldsw + _i * 8192), 16, 0, 0); } while (0)
; #define PG8_LDA(dst, b, h) do { _Pragma("unroll") for (int m = 0; m < 4; ++m) _Pragma("unroll") for (int k = 0; k < 2; ++k) dst[m][k] = *(const LAS bf16x8*)(lds + PG8_SA(b, h) + aoff + m * 2048 + k * 1024); } while (0)
; #define PG8_MMA(ai, bj, At, Bt) do { __builtin_amdgcn_s_setprio(1); _Pragma("unroll") for (int m = 0; m < 4; ++m) _Pragma("unroll") for (int n = 0; n < 2; ++n) _Pragma("unroll") for (int k = 0; k < 2; ++k) \
;         acc[ai][bj][m][n] = __builtin_amdgcn_mfma_f32_16x16x32_bf16(Bt[n][k], At[m][k], acc[ai][bj][m][n], 0, 0, 0); __builtin_amdgcn_s_setprio(0); } while (0)
; #define PG8_WAIT_V(n) asm volatile("s_waitcnt vmcnt(" #n ")" ::: "memory")
; #define PG8_WAIT_L(n) asm volatile("s_waitcnt lgkmcnt(" #n ")" ::: "memory")
; #define PG8_BAR __builtin_amdgcn_s_barrier()
; #define PG8_SCHED __builtin_amdgcn_sched_barrier(0)
; template <class Epi>
; __device__ __forceinline__ void gemm_phase(LAS unsigned char* lds, const int tid, const Gemm g, const StaticOrder& S, const Epi& E) {
;     ...
;             PG8_LDA(At, 1, 1); PG8_STAGE(PG8_SB(1, 0), b3, voffB); PG8_STAGE(PG8_SB(1, 1), b3 + hstepB, voffB); PG8_STAGE(PG8_SA(1, 0), a3, voffA);
;             PG8_WAIT_V(8); PG8_WAIT_L(0); PG8_BAR; PG8_MMA(1, 0, At, B0); PG8_MMA(1, 1, At, B1); PG8_BAR; PG8_SCHED;
	s_add_i32 s24, s59, s38
	v_lshl_add_u64 v[184:185], v[184:185], 0, s[16:17]
	s_mov_b32 m0, s24
	ds_read_b128 v[176:179], v191 offset:49152
	ds_read_b128 v[180:183], v191 offset:50176
	ds_read_b128 v[192:195], v191 offset:51200
	ds_read_b128 v[196:199], v191 offset:52224
	ds_read_b128 v[200:203], v191 offset:53248
	ds_read_b128 v[204:207], v191 offset:54272
	ds_read_b128 v[208:211], v191 offset:55296
	ds_read_b128 v[212:215], v191 offset:56320
	global_load_lds_dwordx4 v[184:185], off
	s_add_i32 m0, s24, 0x2000
	s_add_u32 s24, s28, 0xb0080
	v_lshl_add_u64 v[184:185], v[216:217], 0, s[16:17]
	s_addc_u32 s25, s29, 0
	s_add_i32 s28, s60, s38
	global_load_lds_dwordx4 v[184:185], off
	v_lshl_add_u64 v[184:185], s[24:25], 0, v[130:131]
	s_mov_b32 m0, s28
	s_nop 0
	global_load_lds_dwordx4 v[184:185], off
	v_lshl_add_u64 v[184:185], s[24:25], 0, v[134:135]
	s_add_i32 m0, s28, 0x2000
	s_nop 0
	global_load_lds_dwordx4 v[184:185], off
	v_lshl_add_u64 v[184:185], v[218:219], 0, s[16:17]
	s_mov_b32 m0, s45
	s_nop 0
	global_load_lds_dwordx4 v[184:185], off
	v_lshl_add_u64 v[184:185], v[220:221], 0, s[16:17]
	s_mov_b32 m0, s46
	s_nop 0
	global_load_lds_dwordx4 v[184:185], off
	s_waitcnt vmcnt(8)
	s_waitcnt lgkmcnt(0)
	s_barrier
	s_setprio 1
	v_mfma_f32_16x16x32_bf16 v[60:63], v[144:147], v[176:179], v[60:63]
	v_mfma_f32_16x16x32_bf16 v[56:59], v[152:155], v[176:179], v[56:59]
	v_mfma_f32_16x16x32_bf16 v[52:55], v[144:147], v[192:195], v[52:55]
	v_mfma_f32_16x16x32_bf16 v[48:51], v[152:155], v[192:195], v[48:51]
	v_mfma_f32_16x16x32_bf16 v[40:43], v[144:147], v[200:203], v[40:43]
	v_mfma_f32_16x16x32_bf16 v[32:35], v[152:155], v[200:203], v[32:35]
	v_mfma_f32_16x16x32_bf16 v[24:27], v[144:147], v[208:211], v[24:27]
	v_mfma_f32_16x16x32_bf16 v[16:19], v[152:155], v[208:211], v[16:19]
	v_mfma_f32_16x16x32_bf16 v[60:63], v[148:151], v[180:183], v[60:63]
	v_mfma_f32_16x16x32_bf16 v[56:59], v[156:159], v[180:183], v[56:59]
	v_mfma_f32_16x16x32_bf16 v[52:55], v[148:151], v[196:199], v[52:55]
	v_mfma_f32_16x16x32_bf16 v[48:51], v[156:159], v[196:199], v[48:51]
	v_mfma_f32_16x16x32_bf16 v[40:43], v[148:151], v[204:207], v[40:43]
	v_mfma_f32_16x16x32_bf16 v[32:35], v[156:159], v[204:207], v[32:35]
	v_mfma_f32_16x16x32_bf16 v[24:27], v[148:151], v[212:215], v[24:27]
	v_mfma_f32_16x16x32_bf16 v[16:19], v[156:159], v[212:215], v[16:19]
	v_mfma_f32_16x16x32_bf16 v[44:47], v[160:163], v[176:179], v[44:47]
	v_mfma_f32_16x16x32_bf16 v[36:39], v[168:171], v[176:179], v[36:39]
	v_mfma_f32_16x16x32_bf16 v[28:31], v[160:163], v[192:195], v[28:31]
	ds_read_b128 v[144:147], v189
	v_mfma_f32_16x16x32_bf16 v[20:23], v[168:171], v[192:195], v[20:23]
	v_mfma_f32_16x16x32_bf16 v[12:15], v[160:163], v[200:203], v[12:15]
	v_mfma_f32_16x16x32_bf16 v[8:11], v[168:171], v[200:203], v[8:11]
	ds_read_b128 v[148:151], v189 offset:1024
	v_mfma_f32_16x16x32_bf16 v[4:7], v[160:163], v[208:211], v[4:7]
	v_mfma_f32_16x16x32_bf16 v[0:3], v[168:171], v[208:211], v[0:3]
	v_mfma_f32_16x16x32_bf16 v[44:47], v[164:167], v[180:183], v[44:47]
	ds_read_b128 v[152:155], v189 offset:2048
	v_mfma_f32_16x16x32_bf16 v[36:39], v[172:175], v[180:183], v[36:39]
	v_mfma_f32_16x16x32_bf16 v[28:31], v[164:167], v[196:199], v[28:31]
	v_mfma_f32_16x16x32_bf16 v[20:23], v[172:175], v[196:199], v[20:23]
	ds_read_b128 v[156:159], v189 offset:3072
	v_mfma_f32_16x16x32_bf16 v[12:15], v[164:167], v[204:207], v[12:15]
	v_mfma_f32_16x16x32_bf16 v[8:11], v[172:175], v[204:207], v[8:11]
	v_mfma_f32_16x16x32_bf16 v[4:7], v[164:167], v[212:215], v[4:7]
	v_mfma_f32_16x16x32_bf16 v[0:3], v[172:175], v[212:215], v[0:3]
	s_setprio 0
	s_barrier
; #define PG8_BAR __builtin_amdgcn_s_barrier()
; template <class Epi>
; __device__ __forceinline__ void gemm_phase(LAS unsigned char* lds, const int tid, const Gemm g, const StaticOrder& S, const Epi& E) {
;     ...
;         for (int t = 0; t < nt; t += 2) {
;     ...
;         }
;         if (wr == 0) PG8_BAR;
;         E(acc, cur, wr, wc, fr, fq);
;     __device__ __forceinline__ void operator()(const Acc& acc, const Unit& u, int wr, int wc, int fr, int fq) const {
;     ...
;                     const f32x4 h0 = hv[m][bj][0] + acc[ai][bj][m][0] * scale, h1 = hv[m][bj][1] + acc[ai][bj][m][1] * scale;
	s_add_u32 s56, s56, 0x100
	s_addc_u32 s57, s57, 0
	s_cmp_ge_i32 s58, s44
	s_mov_b64 s[24:25], s[26:27]
	s_mov_b32 s28, s58
	s_cbranch_scc0 .LBB0_906
	s_waitcnt lgkmcnt(0)
	v_pk_mul_f32 v[154:155], v[126:127], 0.5 op_sel_hi:[1,0]
	v_pk_mul_f32 v[156:157], v[124:125], 0.5 op_sel_hi:[1,0]
	v_pk_mul_f32 v[158:159], v[122:123], 0.5 op_sel_hi:[1,0]
	v_pk_mul_f32 v[160:161], v[120:121], 0.5 op_sel_hi:[1,0]
	v_pk_mul_f32 v[168:169], v[110:111], 0.5 op_sel_hi:[1,0]
	v_pk_mul_f32 v[166:167], v[108:109], 0.5 op_sel_hi:[1,0]
	v_pk_mul_f32 v[164:165], v[102:103], 0.5 op_sel_hi:[1,0]
	v_pk_mul_f32 v[162:163], v[100:101], 0.5 op_sel_hi:[1,0]
	v_pk_mul_f32 v[152:153], v[118:119], 0.5 op_sel_hi:[1,0]
	v_pk_mul_f32 v[150:151], v[116:117], 0.5 op_sel_hi:[1,0]
	v_pk_mul_f32 v[148:149], v[114:115], 0.5 op_sel_hi:[1,0]
	v_pk_mul_f32 v[146:147], v[112:113], 0.5 op_sel_hi:[1,0]
	v_pk_mul_f32 v[144:145], v[94:95], 0.5 op_sel_hi:[1,0]
	v_pk_mul_f32 v[126:127], v[92:93], 0.5 op_sel_hi:[1,0]
	v_pk_mul_f32 v[124:125], v[86:87], 0.5 op_sel_hi:[1,0]
	v_pk_mul_f32 v[122:123], v[84:85], 0.5 op_sel_hi:[1,0]
	v_pk_mul_f32 v[120:121], v[106:107], 0.5 op_sel_hi:[1,0]
	v_pk_mul_f32 v[118:119], v[104:105], 0.5 op_sel_hi:[1,0]
	v_pk_mul_f32 v[116:117], v[98:99], 0.5 op_sel_hi:[1,0]
	v_pk_mul_f32 v[114:115], v[96:97], 0.5 op_sel_hi:[1,0]
	v_pk_mul_f32 v[112:113], v[78:79], 0.5 op_sel_hi:[1,0]
	v_pk_mul_f32 v[110:111], v[76:77], 0.5 op_sel_hi:[1,0]
	v_pk_mul_f32 v[108:109], v[74:75], 0.5 op_sel_hi:[1,0]
	v_pk_mul_f32 v[106:107], v[72:73], 0.5 op_sel_hi:[1,0]
	v_pk_mul_f32 v[104:105], v[90:91], 0.5 op_sel_hi:[1,0]
	v_pk_mul_f32 v[102:103], v[88:89], 0.5 op_sel_hi:[1,0]
	v_pk_mul_f32 v[100:101], v[82:83], 0.5 op_sel_hi:[1,0]
	v_pk_mul_f32 v[98:99], v[80:81], 0.5 op_sel_hi:[1,0]
	v_pk_mul_f32 v[96:97], v[70:71], 0.5 op_sel_hi:[1,0]
	v_pk_mul_f32 v[94:95], v[68:69], 0.5 op_sel_hi:[1,0]
	v_pk_mul_f32 v[92:93], v[66:67], 0.5 op_sel_hi:[1,0]
	v_pk_mul_f32 v[90:91], v[64:65], 0.5 op_sel_hi:[1,0]
	v_pk_mul_f32 v[72:73], v[62:63], 0.5 op_sel_hi:[1,0]
	v_pk_mul_f32 v[74:75], v[60:61], 0.5 op_sel_hi:[1,0]
	v_pk_mul_f32 v[76:77], v[58:59], 0.5 op_sel_hi:[1,0]
	v_pk_mul_f32 v[78:79], v[56:57], 0.5 op_sel_hi:[1,0]
	v_pk_mul_f32 v[86:87], v[46:47], 0.5 op_sel_hi:[1,0]
	v_pk_mul_f32 v[84:85], v[44:45], 0.5 op_sel_hi:[1,0]
	v_pk_mul_f32 v[82:83], v[38:39], 0.5 op_sel_hi:[1,0]
	v_pk_mul_f32 v[80:81], v[36:37], 0.5 op_sel_hi:[1,0]
	v_pk_mul_f32 v[70:71], v[54:55], 0.5 op_sel_hi:[1,0]
	v_pk_mul_f32 v[68:69], v[52:53], 0.5 op_sel_hi:[1,0]
	v_pk_mul_f32 v[66:67], v[50:51], 0.5 op_sel_hi:[1,0]
	v_pk_mul_f32 v[64:65], v[48:49], 0.5 op_sel_hi:[1,0]
	v_pk_mul_f32 v[62:63], v[30:31], 0.5 op_sel_hi:[1,0]
	v_pk_mul_f32 v[60:61], v[28:29], 0.5 op_sel_hi:[1,0]
	v_pk_mul_f32 v[58:59], v[22:23], 0.5 op_sel_hi:[1,0]
	v_pk_mul_f32 v[56:57], v[20:21], 0.5 op_sel_hi:[1,0]
	v_pk_mul_f32 v[54:55], v[42:43], 0.5 op_sel_hi:[1,0]
	v_pk_mul_f32 v[52:53], v[40:41], 0.5 op_sel_hi:[1,0]
	v_pk_mul_f32 v[50:51], v[34:35], 0.5 op_sel_hi:[1,0]
	v_pk_mul_f32 v[48:49], v[32:33], 0.5 op_sel_hi:[1,0]
	v_pk_mul_f32 v[46:47], v[14:15], 0.5 op_sel_hi:[1,0]
	v_pk_mul_f32 v[44:45], v[12:13], 0.5 op_sel_hi:[1,0]
	v_pk_mul_f32 v[42:43], v[10:11], 0.5 op_sel_hi:[1,0]
	v_pk_mul_f32 v[40:41], v[8:9], 0.5 op_sel_hi:[1,0]
	v_pk_mul_f32 v[38:39], v[26:27], 0.5 op_sel_hi:[1,0]
	v_pk_mul_f32 v[36:37], v[24:25], 0.5 op_sel_hi:[1,0]
	v_pk_mul_f32 v[34:35], v[18:19], 0.5 op_sel_hi:[1,0]
	v_pk_mul_f32 v[32:33], v[16:17], 0.5 op_sel_hi:[1,0]
	v_pk_mul_f32 v[30:31], v[6:7], 0.5 op_sel_hi:[1,0]
	v_pk_mul_f32 v[28:29], v[4:5], 0.5 op_sel_hi:[1,0]
	v_pk_mul_f32 v[26:27], v[2:3], 0.5 op_sel_hi:[1,0]
	v_pk_mul_f32 v[24:25], v[0:1], 0.5 op_sel_hi:[1,0]
